# barrier waiters poll the top-level arrival counter (>= 8*idx) instead of the per-group release flag: one memory hop less after the last arrival
# speedup vs baseline: 1.0154x; 1.0023x over previous
; DI void grid_barrier(const Ctx& c, unsigned idx) {
;     ...
;     while (__hip_atomic_load(bar + 64 * (9 + grp), __ATOMIC_RELAXED, __HIP_MEMORY_SCOPE_AGENT) < idx) __builtin_amdgcn_s_sleep(1);
;     __builtin_amdgcn_fence(__ATOMIC_ACQUIRE, "agent");
.LBB0_340:
	s_or_b64 exec, exec, s[4:5]
	v_mov_b32_e32 v0, 0
	s_add_u32 s100, s92, 0x1fe00000
	s_addc_u32 s101, s93, 0
	global_load_dword v1, v0, s[100:101] sc1
	s_waitcnt vmcnt(0)
	v_cmp_lt_u32_e32 vcc, 7, v1
	s_cbranch_vccnz .LBB0_342
.LBB0_341:
	s_sleep 1
	global_load_dword v1, v0, s[100:101] sc1
	s_waitcnt vmcnt(0)
	v_cmp_gt_u32_e32 vcc, 8, v1
	s_cbranch_vccnz .LBB0_341

; DI void grid_barrier(const Ctx& c, unsigned idx) {
;     ...
;     while (__hip_atomic_load(bar + 64 * (9 + grp), __ATOMIC_RELAXED, __HIP_MEMORY_SCOPE_AGENT) < idx) __builtin_amdgcn_s_sleep(1);
;     __builtin_amdgcn_fence(__ATOMIC_ACQUIRE, "agent");
.LBB0_545:
	s_or_b64 exec, exec, s[4:5]
	v_mov_b32_e32 v0, 0
	s_add_u32 s100, s92, 0x1fe00000
	s_addc_u32 s101, s93, 0
	global_load_dword v1, v0, s[100:101] sc1
	s_waitcnt vmcnt(0)
	v_cmp_lt_u32_e32 vcc, 15, v1
	s_cbranch_vccnz .LBB0_547
.LBB0_546:
	s_sleep 1
	global_load_dword v1, v0, s[100:101] sc1
	s_waitcnt vmcnt(0)
	v_cmp_gt_u32_e32 vcc, 16, v1
	s_cbranch_vccnz .LBB0_546

; DI void grid_barrier(const Ctx& c, unsigned idx) {
;     ...
;     while (__hip_atomic_load(bar + 64 * (9 + grp), __ATOMIC_RELAXED, __HIP_MEMORY_SCOPE_AGENT) < idx) __builtin_amdgcn_s_sleep(1);
;     __builtin_amdgcn_fence(__ATOMIC_ACQUIRE, "agent");
.LBB0_596:
	s_or_b64 exec, exec, s[4:5]
	v_mov_b32_e32 v0, 0
	s_add_u32 s100, s92, 0x1fe00000
	s_addc_u32 s101, s93, 0
	global_load_dword v1, v0, s[100:101] sc1
	s_waitcnt vmcnt(0)
	v_cmp_lt_u32_e32 vcc, 23, v1
	s_cbranch_vccnz .LBB0_598
.LBB0_597:
	s_sleep 1
	global_load_dword v1, v0, s[100:101] sc1
	s_waitcnt vmcnt(0)
	v_cmp_gt_u32_e32 vcc, 24, v1
	s_cbranch_vccnz .LBB0_597

; DI void grid_barrier(const Ctx& c, unsigned idx) {
;     ...
;     while (__hip_atomic_load(bar + 64 * (9 + grp), __ATOMIC_RELAXED, __HIP_MEMORY_SCOPE_AGENT) < idx) __builtin_amdgcn_s_sleep(1);
;     __builtin_amdgcn_fence(__ATOMIC_ACQUIRE, "agent");
.LBB0_823:
	s_or_b64 exec, exec, s[4:5]
	v_mov_b32_e32 v0, 0
	s_add_u32 s100, s92, 0x1fe00000
	s_addc_u32 s101, s93, 0
	global_load_dword v1, v0, s[100:101] sc1
	s_waitcnt vmcnt(0)
	v_cmp_lt_u32_e32 vcc, 31, v1
	s_cbranch_vccnz .LBB0_825
.LBB0_824:
	s_sleep 1
	global_load_dword v1, v0, s[100:101] sc1
	s_waitcnt vmcnt(0)
	v_cmp_gt_u32_e32 vcc, 32, v1
	s_cbranch_vccnz .LBB0_824

; DI void grid_barrier(const Ctx& c, unsigned idx) {
;     ...
;     while (__hip_atomic_load(bar + 64 * (9 + grp), __ATOMIC_RELAXED, __HIP_MEMORY_SCOPE_AGENT) < idx) __builtin_amdgcn_s_sleep(1);
;     __builtin_amdgcn_fence(__ATOMIC_ACQUIRE, "agent");
.LBB0_851:
	s_or_b64 exec, exec, s[4:5]
	v_mov_b32_e32 v0, 0
	s_add_u32 s100, s92, 0x1fe00000
	s_addc_u32 s101, s93, 0
	global_load_dword v1, v0, s[100:101] sc1
	s_waitcnt vmcnt(0)
	v_cmp_lt_u32_e32 vcc, 39, v1
	s_cbranch_vccnz .LBB0_853
.LBB0_852:
	s_sleep 1
	global_load_dword v1, v0, s[100:101] sc1
	s_waitcnt vmcnt(0)
	v_cmp_gt_u32_e32 vcc, 40, v1
	s_cbranch_vccnz .LBB0_852

; DI void grid_barrier(const Ctx& c, unsigned idx) {
;     ...
;     while (__hip_atomic_load(bar + 64 * (9 + grp), __ATOMIC_RELAXED, __HIP_MEMORY_SCOPE_AGENT) < idx) __builtin_amdgcn_s_sleep(1);
;     __builtin_amdgcn_fence(__ATOMIC_ACQUIRE, "agent");
.LBB0_879:
	s_or_b64 exec, exec, s[4:5]
	v_mov_b32_e32 v0, 0
	s_add_u32 s100, s92, 0x1fe00000
	s_addc_u32 s101, s93, 0
	global_load_dword v1, v0, s[100:101] sc1
	s_waitcnt vmcnt(0)
	v_cmp_lt_u32_e32 vcc, 47, v1
	s_cbranch_vccnz .LBB0_881
.LBB0_880:
	s_sleep 1
	global_load_dword v1, v0, s[100:101] sc1
	s_waitcnt vmcnt(0)
	v_cmp_gt_u32_e32 vcc, 48, v1
	s_cbranch_vccnz .LBB0_880

; DI void grid_barrier(const Ctx& c, unsigned idx) {
;     ...
;     while (__hip_atomic_load(bar + 64 * (9 + grp), __ATOMIC_RELAXED, __HIP_MEMORY_SCOPE_AGENT) < idx) __builtin_amdgcn_s_sleep(1);
;     __builtin_amdgcn_fence(__ATOMIC_ACQUIRE, "agent");
.LBB0_897:
	s_or_b64 exec, exec, s[6:7]
	v_mov_b32_e32 v0, 0
	s_add_u32 s100, s92, 0x1fe00000
	s_addc_u32 s101, s93, 0
	global_load_dword v1, v0, s[100:101] sc1
	s_waitcnt vmcnt(0)
	v_cmp_lt_u32_e32 vcc, 55, v1
	s_cbranch_vccnz .LBB0_899
.LBB0_898:
	s_sleep 1
	global_load_dword v1, v0, s[100:101] sc1
	s_waitcnt vmcnt(0)
	v_cmp_gt_u32_e32 vcc, 56, v1
	s_cbranch_vccnz .LBB0_898

; DI void grid_barrier(const Ctx& c, unsigned idx) {
;     ...
;     while (__hip_atomic_load(bar + 64 * (9 + grp), __ATOMIC_RELAXED, __HIP_MEMORY_SCOPE_AGENT) < idx) __builtin_amdgcn_s_sleep(1);
;     __builtin_amdgcn_fence(__ATOMIC_ACQUIRE, "agent");
.LBB0_925:
	s_or_b64 exec, exec, s[4:5]
	v_mov_b32_e32 v0, 0
	s_add_u32 s100, s92, 0x1fe00000
	s_addc_u32 s101, s93, 0
	global_load_dword v1, v0, s[100:101] sc1
	s_waitcnt vmcnt(0)
	v_cmp_lt_u32_e32 vcc, 63, v1
	s_cbranch_vccnz .LBB0_927
.LBB0_926:
	s_sleep 1
	global_load_dword v1, v0, s[100:101] sc1
	s_waitcnt vmcnt(0)
	v_cmp_gt_u32_e32 vcc, 64, v1
	s_cbranch_vccnz .LBB0_926

; DI void grid_barrier(const Ctx& c, unsigned idx) {
;     ...
;     while (__hip_atomic_load(bar + 64 * (9 + grp), __ATOMIC_RELAXED, __HIP_MEMORY_SCOPE_AGENT) < idx) __builtin_amdgcn_s_sleep(1);
;     __builtin_amdgcn_fence(__ATOMIC_ACQUIRE, "agent");
.LBB0_953:
	s_or_b64 exec, exec, s[4:5]
	v_mov_b32_e32 v0, 0
	s_add_u32 s100, s92, 0x1fe00000
	s_addc_u32 s101, s93, 0
	global_load_dword v1, v0, s[100:101] sc1
	s_waitcnt vmcnt(0)
	v_cmp_lt_u32_e32 vcc, 71, v1
	s_cbranch_vccnz .LBB0_955
.LBB0_954:
	s_sleep 1
	global_load_dword v1, v0, s[100:101] sc1
	s_waitcnt vmcnt(0)
	v_cmp_gt_u32_e32 vcc, 72, v1
	s_cbranch_vccnz .LBB0_954

; DI void grid_barrier(const Ctx& c, unsigned idx) {
;     ...
;     while (__hip_atomic_load(bar + 64 * (9 + grp), __ATOMIC_RELAXED, __HIP_MEMORY_SCOPE_AGENT) < idx) __builtin_amdgcn_s_sleep(1);
;     __builtin_amdgcn_fence(__ATOMIC_ACQUIRE, "agent");
.LBB0_971:
	s_or_b64 exec, exec, s[6:7]
	v_mov_b32_e32 v0, 0
	s_add_u32 s100, s92, 0x1fe00000
	s_addc_u32 s101, s93, 0
	global_load_dword v1, v0, s[100:101] sc1
	s_waitcnt vmcnt(0)
	v_cmp_lt_u32_e32 vcc, 79, v1
	s_cbranch_vccnz .LBB0_973
.LBB0_972:
	s_sleep 1
	global_load_dword v1, v0, s[100:101] sc1
	s_waitcnt vmcnt(0)
	v_cmp_gt_u32_e32 vcc, 80, v1
	s_cbranch_vccnz .LBB0_972

; DI void grid_barrier(const Ctx& c, unsigned idx) {
;     ...
;     while (__hip_atomic_load(bar + 64 * (9 + grp), __ATOMIC_RELAXED, __HIP_MEMORY_SCOPE_AGENT) < idx) __builtin_amdgcn_s_sleep(1);
;     __builtin_amdgcn_fence(__ATOMIC_ACQUIRE, "agent");
.LBB0_1255:
	s_or_b64 exec, exec, s[4:5]
	v_mov_b32_e32 v0, 0
	s_add_u32 s100, s92, 0x1fe00000
	s_addc_u32 s101, s93, 0
	global_load_dword v1, v0, s[100:101] sc1
	s_waitcnt vmcnt(0)
	v_cmp_lt_u32_e32 vcc, 87, v1
	s_cbranch_vccnz .LBB0_1257
.LBB0_1256:
	s_sleep 1
	global_load_dword v1, v0, s[100:101] sc1
	s_waitcnt vmcnt(0)
	v_cmp_gt_u32_e32 vcc, 88, v1
	s_cbranch_vccnz .LBB0_1256

; DI void grid_barrier(const Ctx& c, unsigned idx) {
;     ...
;     while (__hip_atomic_load(bar + 64 * (9 + grp), __ATOMIC_RELAXED, __HIP_MEMORY_SCOPE_AGENT) < idx) __builtin_amdgcn_s_sleep(1);
;     __builtin_amdgcn_fence(__ATOMIC_ACQUIRE, "agent");
.LBB0_1720:
	s_or_b64 exec, exec, s[4:5]
	v_mov_b32_e32 v0, 0
	s_add_u32 s100, s92, 0x1fe00000
	s_addc_u32 s101, s93, 0
	global_load_dword v1, v0, s[100:101] sc1
	s_waitcnt vmcnt(0)
	v_cmp_lt_u32_e32 vcc, 95, v1
	s_cbranch_vccnz .LBB0_1722
.LBB0_1721:
	s_sleep 1
	global_load_dword v1, v0, s[100:101] sc1
	s_waitcnt vmcnt(0)
	v_cmp_gt_u32_e32 vcc, 96, v1
	s_cbranch_vccnz .LBB0_1721

; DI void grid_barrier(const Ctx& c, unsigned idx) {
;     ...
;     while (__hip_atomic_load(bar + 64 * (9 + grp), __ATOMIC_RELAXED, __HIP_MEMORY_SCOPE_AGENT) < idx) __builtin_amdgcn_s_sleep(1);
;     __builtin_amdgcn_fence(__ATOMIC_ACQUIRE, "agent");
.LBB0_1812:
	s_or_b64 exec, exec, s[4:5]
	v_mov_b32_e32 v0, 0
	s_add_u32 s100, s92, 0x1fe00000
	s_addc_u32 s101, s93, 0
	global_load_dword v1, v0, s[100:101] sc1
	s_waitcnt vmcnt(0)
	v_cmp_lt_u32_e32 vcc, 103, v1
	s_cbranch_vccnz .LBB0_1814
.LBB0_1813:
	s_sleep 1
	global_load_dword v1, v0, s[100:101] sc1
	s_waitcnt vmcnt(0)
	v_cmp_gt_u32_e32 vcc, 104, v1
	s_cbranch_vccnz .LBB0_1813

; DI void grid_barrier(const Ctx& c, unsigned idx) {
;     ...
;     while (__hip_atomic_load(bar + 64 * (9 + grp), __ATOMIC_RELAXED, __HIP_MEMORY_SCOPE_AGENT) < idx) __builtin_amdgcn_s_sleep(1);
;     __builtin_amdgcn_fence(__ATOMIC_ACQUIRE, "agent");
.LBB0_1840:
	s_or_b64 exec, exec, s[4:5]
	v_mov_b32_e32 v0, 0
	s_add_u32 s100, s92, 0x1fe00000
	s_addc_u32 s101, s93, 0
	global_load_dword v1, v0, s[100:101] sc1
	s_waitcnt vmcnt(0)
	v_cmp_lt_u32_e32 vcc, 111, v1
	s_cbranch_vccnz .LBB0_1842
.LBB0_1841:
	s_sleep 1
	global_load_dword v1, v0, s[100:101] sc1
	s_waitcnt vmcnt(0)
	v_cmp_gt_u32_e32 vcc, 112, v1
	s_cbranch_vccnz .LBB0_1841

; DI void grid_barrier(const Ctx& c, unsigned idx) {
;     ...
;     while (__hip_atomic_load(bar + 64 * (9 + grp), __ATOMIC_RELAXED, __HIP_MEMORY_SCOPE_AGENT) < idx) __builtin_amdgcn_s_sleep(1);
;     __builtin_amdgcn_fence(__ATOMIC_ACQUIRE, "agent");
.LBB0_1868:
	s_or_b64 exec, exec, s[4:5]
	v_mov_b32_e32 v0, 0
	s_add_u32 s100, s92, 0x1fe00000
	s_addc_u32 s101, s93, 0
	global_load_dword v1, v0, s[100:101] sc1
	s_waitcnt vmcnt(0)
	v_cmp_lt_u32_e32 vcc, 119, v1
	s_cbranch_vccnz .LBB0_1870
.LBB0_1869:
	s_sleep 1
	global_load_dword v1, v0, s[100:101] sc1
	s_waitcnt vmcnt(0)
	v_cmp_gt_u32_e32 vcc, 120, v1
	s_cbranch_vccnz .LBB0_1869

; DI void grid_barrier(const Ctx& c, unsigned idx) {
;     ...
;     while (__hip_atomic_load(bar + 64 * (9 + grp), __ATOMIC_RELAXED, __HIP_MEMORY_SCOPE_AGENT) < idx) __builtin_amdgcn_s_sleep(1);
;     __builtin_amdgcn_fence(__ATOMIC_ACQUIRE, "agent");
.LBB0_1886:
	s_or_b64 exec, exec, s[6:7]
	v_mov_b32_e32 v0, 0
	s_add_u32 s100, s92, 0x1fe00000
	s_addc_u32 s101, s93, 0
	global_load_dword v1, v0, s[100:101] sc1
	s_waitcnt vmcnt(0)
	v_cmp_lt_u32_e32 vcc, 127, v1
	s_cbranch_vccnz .LBB0_1888
.LBB0_1887:
	s_sleep 1
	global_load_dword v1, v0, s[100:101] sc1
	s_waitcnt vmcnt(0)
	v_cmp_gt_u32_e32 vcc, 128, v1
	s_cbranch_vccnz .LBB0_1887

; DI void grid_barrier(const Ctx& c, unsigned idx) {
;     ...
;     while (__hip_atomic_load(bar + 64 * (9 + grp), __ATOMIC_RELAXED, __HIP_MEMORY_SCOPE_AGENT) < idx) __builtin_amdgcn_s_sleep(1);
;     __builtin_amdgcn_fence(__ATOMIC_ACQUIRE, "agent");
.LBB0_1914:
	s_or_b64 exec, exec, s[4:5]
	v_mov_b32_e32 v0, 0
	s_add_u32 s100, s92, 0x1fe00000
	s_addc_u32 s101, s93, 0
	global_load_dword v1, v0, s[100:101] sc1
	s_waitcnt vmcnt(0)
	v_cmp_lt_u32_e32 vcc, 135, v1
	s_cbranch_vccnz .LBB0_1916
.LBB0_1915:
	s_sleep 1
	global_load_dword v1, v0, s[100:101] sc1
	s_waitcnt vmcnt(0)
	v_cmp_gt_u32_e32 vcc, 136, v1
	s_cbranch_vccnz .LBB0_1915

; DI void grid_barrier(const Ctx& c, unsigned idx) {
;     ...
;     while (__hip_atomic_load(bar + 64 * (9 + grp), __ATOMIC_RELAXED, __HIP_MEMORY_SCOPE_AGENT) < idx) __builtin_amdgcn_s_sleep(1);
;     __builtin_amdgcn_fence(__ATOMIC_ACQUIRE, "agent");
.LBB0_1942:
	s_or_b64 exec, exec, s[4:5]
	v_mov_b32_e32 v0, 0
	s_add_u32 s100, s92, 0x1fe00000
	s_addc_u32 s101, s93, 0
	global_load_dword v1, v0, s[100:101] sc1
	s_waitcnt vmcnt(0)
	v_cmp_lt_u32_e32 vcc, 143, v1
	s_cbranch_vccnz .LBB0_1944
.LBB0_1943:
	s_sleep 1
	global_load_dword v1, v0, s[100:101] sc1
	s_waitcnt vmcnt(0)
	v_cmp_gt_u32_e32 vcc, 144, v1
	s_cbranch_vccnz .LBB0_1943

; DI void grid_barrier(const Ctx& c, unsigned idx) {
;     ...
;     while (__hip_atomic_load(bar + 64 * (9 + grp), __ATOMIC_RELAXED, __HIP_MEMORY_SCOPE_AGENT) < idx) __builtin_amdgcn_s_sleep(1);
;     __builtin_amdgcn_fence(__ATOMIC_ACQUIRE, "agent");
.LBB0_1960:
	s_or_b64 exec, exec, s[6:7]
	v_mov_b32_e32 v0, 0
	s_add_u32 s100, s92, 0x1fe00000
	s_addc_u32 s101, s93, 0
	global_load_dword v1, v0, s[100:101] sc1
	s_waitcnt vmcnt(0)
	v_cmp_lt_u32_e32 vcc, 151, v1
	s_cbranch_vccnz .LBB0_1962
.LBB0_1961:
	s_sleep 1
	global_load_dword v1, v0, s[100:101] sc1
	s_waitcnt vmcnt(0)
	v_cmp_gt_u32_e32 vcc, 152, v1
	s_cbranch_vccnz .LBB0_1961
